# item-tail load balancing: the extra gla1/lru1 items go to the workgroups whose attention share holds the cheaper 2-wave sample item
# baseline (speedup 1.0000x reference)
; #define VB() (2 * B + (TID512() >> 8))
; #define HS() (smem + (TID512() >> 8) * HALF_LDS)
; __global__ void __launch_bounds__(512, 2) mega(Params p) {
;     ...
;     if (ONLY < 0 || ONLY == 13) for (int it = VB(); it < NGI; it += vG) gla1_item(p, l, it, HS());
.LBB0_1390:
	v_mov_b32_e32 v0, v184
	v_readlane_b32 s4, v251, 5
	v_ashrrev_i32_e32 v0, 8, v0
	v_readlane_b32 s5, v251, 6
	v_add_u32_e32 v0, s4, v0
	v_add_u32_e32 v0, 0x80, v0
	v_and_b32_e32 v0, 0x1ff, v0
	s_movk_i32 s4, 0x840
	v_cmp_gt_i32_e32 vcc, s4, v0
	s_and_saveexec_b64 s[4:5], vcc
	s_cbranch_execz .LBB0_1451
	v_readlane_b32 s8, v254, 39
	v_readlane_b32 s9, v254, 40
	v_readlane_b32 s36, v254, 21
	s_lshl_b64 s[6:7], s[8:9], 14
	v_readlane_b32 s38, v254, 23
	v_readlane_b32 s39, v254, 24
	s_add_u32 s6, s38, s6
	v_readlane_b32 s40, v254, 25
	s_addc_u32 s7, s39, s7
	s_lshl_b64 s[8:9], s[8:9], 10
	v_readlane_b32 s41, v254, 26
	s_add_u32 s8, s40, s8
	s_addc_u32 s9, s41, s9
	s_mov_b64 s[12:13], 0
	v_readlane_b32 s37, v254, 22
	v_readlane_b32 s42, v254, 27
	v_readlane_b32 s43, v254, 28
	s_branch .LBB0_1393

; #define VB() (2 * B + (TID512() >> 8))
; #define HS() (smem + (TID512() >> 8) * HALF_LDS)
; __global__ void __launch_bounds__(512, 2) mega(Params p) {
;     ...
;     if (ONLY < 0 || ONLY == 14) for (int it = VB(); it < L1_ITEMS; it += vG) lru1_item(p, l, it, HS());
.LBB0_1451:
	s_or_b64 exec, exec, s[4:5]
	v_mov_b32_e32 v0, v184
	v_readlane_b32 s4, v251, 5
	v_ashrrev_i32_e32 v0, 8, v0
	v_readlane_b32 s5, v251, 6
	v_add_u32_e32 v2, s4, v0
	v_add_u32_e32 v2, 0x80, v2
	v_and_b32_e32 v2, 0x1ff, v2
	v_cmp_gt_i32_e32 vcc, s2, v2
	s_mov_b64 s[4:5], exec
	v_writelane_b32 v254, s4, 62
	s_nop 1
	v_writelane_b32 v254, s5, 63
	s_and_b64 s[4:5], s[4:5], vcc
	s_mov_b64 exec, s[4:5]
	s_cbranch_execz .LBB0_1716
	v_readlane_b32 s8, v254, 39
	v_readlane_b32 s9, v254, 40
	s_lshl_b64 s[4:5], s[8:9], 13
	v_readlane_b32 s28, v254, 9
	v_readlane_b32 s29, v254, 10
	s_add_u32 s26, s28, s4
	s_addc_u32 s27, s29, s5
	v_readlane_b32 s4, v254, 60
	v_readlane_b32 s5, v254, 61
	v_readlane_b32 s30, v254, 11
	s_lshl_b64 s[6:7], s[4:5], 2
	v_readlane_b32 s31, v254, 12
	s_add_u32 s28, s30, s6
	s_addc_u32 s29, s31, s7
	s_lshl_b64 s[30:31], s[8:9], 4
	v_readlane_b32 s4, v254, 57
	s_add_u32 s34, s4, 0x2910000
	v_readlane_b32 s5, v254, 58
	s_addc_u32 s35, s5, 0
	s_add_u32 s36, s4, 0x2920000
	s_addc_u32 s37, s5, 0
	v_readlane_b32 s4, v254, 7
	v_readlane_b32 s5, v254, 8
	s_add_u32 s12, s4, s6
	s_addc_u32 s13, s5, s7
	v_readlane_b32 s8, v254, 13
	v_readlane_b32 s9, v254, 14
	s_add_u32 s4, s8, s6
	v_readlane_b32 s10, v254, 15
	s_addc_u32 s5, s9, s7
	v_readlane_b32 s11, v254, 16
	s_add_u32 s6, s10, s6
	s_addc_u32 s7, s11, s7
	s_mov_b64 s[8:9], 0
	s_branch .LBB0_1454
